# v19 + builders moved to last two WGs + main transpose loop loads batched + conditioning SiLU loop batched (two rounds of ten loads in flight)
# speedup vs baseline: 1.0037x; 1.0024x over previous
; __device__ __forceinline__ float silu_f(float x) { return x * sigm_f(x); }
; __global__ void __launch_bounds__(512, 2) mega_fwd(Args args) {
;     ...
;                 for (int i = tid; i < 5 * DM; i += 512) { const float v = i < 4 * DM ? args.in[1][i] : args.in[3][i - 4 * DM]; sc[i] = silu_f(v); }
.LBB0_735:
	s_movk_i32 s2, 0x2800
	v_cmp_gt_i32_e32 vcc, s2, v186
	s_and_saveexec_b64 s[12:13], vcc
	v_readlane_b32 s44, v253, 61
	v_readlane_b32 s46, v253, 63
	v_readlane_b32 s47, v254, 0
	v_readlane_b32 s50, v254, 3
	v_readlane_b32 s51, v254, 4
	v_readlane_b32 s45, v253, 62
	v_readlane_b32 s48, v254, 1
	v_readlane_b32 s49, v254, 2
	v_readlane_b32 s52, v254, 5
	v_readlane_b32 s53, v254, 6
	v_readlane_b32 s54, v254, 7
	v_readlane_b32 s55, v254, 8
	v_readlane_b32 s56, v254, 9
	v_readlane_b32 s57, v254, 10
	v_readlane_b32 s58, v254, 11
	v_readlane_b32 s59, v254, 12
	s_cbranch_execz .LBB0_738
	v_ashrrev_i32_e32 v187, 31, v186
	v_lshl_add_u64 v[0:1], v[186:187], 2, s[46:47]
	v_lshl_add_u32 v2, v186, 2, 0
	s_mov_b64 s[14:15], 0
	v_mov_b32_e32 v176, v186
	s_movk_i32 s2, 0x8000
	s_mov_b32 s3, -1
	v_lshl_add_u64 v[4:5], v[176:177], 2, s[50:51]
	v_cmp_gt_i32_e32 vcc, s84, v176
	v_lshl_add_u64 v[4:5], v[4:5], 0, s[2:3]
	s_nop 1
	v_cndmask_b32_e32 v5, v5, v1, vcc
	v_cndmask_b32_e32 v4, v4, v0, vcc
	global_load_dword v52, v[4:5], off
	v_add_u32_e32 v176, 0x200, v176
	v_lshl_add_u64 v[0:1], v[0:1], 0, s[72:73]
	v_lshl_add_u64 v[4:5], v[176:177], 2, s[50:51]
	v_cmp_gt_i32_e32 vcc, s84, v176
	v_lshl_add_u64 v[4:5], v[4:5], 0, s[2:3]
	s_nop 1
	v_cndmask_b32_e32 v5, v5, v1, vcc
	v_cndmask_b32_e32 v4, v4, v0, vcc
	global_load_dword v54, v[4:5], off
	v_add_u32_e32 v176, 0x200, v176
	v_lshl_add_u64 v[0:1], v[0:1], 0, s[72:73]
	v_lshl_add_u64 v[4:5], v[176:177], 2, s[50:51]
	v_cmp_gt_i32_e32 vcc, s84, v176
	v_lshl_add_u64 v[4:5], v[4:5], 0, s[2:3]
	s_nop 1
	v_cndmask_b32_e32 v5, v5, v1, vcc
	v_cndmask_b32_e32 v4, v4, v0, vcc
	global_load_dword v56, v[4:5], off
	v_add_u32_e32 v176, 0x200, v176
	v_lshl_add_u64 v[0:1], v[0:1], 0, s[72:73]
	v_lshl_add_u64 v[4:5], v[176:177], 2, s[50:51]
	v_cmp_gt_i32_e32 vcc, s84, v176
	v_lshl_add_u64 v[4:5], v[4:5], 0, s[2:3]
	s_nop 1
	v_cndmask_b32_e32 v5, v5, v1, vcc
	v_cndmask_b32_e32 v4, v4, v0, vcc
	global_load_dword v58, v[4:5], off
	v_add_u32_e32 v176, 0x200, v176
	v_lshl_add_u64 v[0:1], v[0:1], 0, s[72:73]
	v_lshl_add_u64 v[4:5], v[176:177], 2, s[50:51]
	v_cmp_gt_i32_e32 vcc, s84, v176
	v_lshl_add_u64 v[4:5], v[4:5], 0, s[2:3]
	s_nop 1
	v_cndmask_b32_e32 v5, v5, v1, vcc
	v_cndmask_b32_e32 v4, v4, v0, vcc
	global_load_dword v60, v[4:5], off
	v_add_u32_e32 v176, 0x200, v176
	v_lshl_add_u64 v[0:1], v[0:1], 0, s[72:73]
	v_lshl_add_u64 v[4:5], v[176:177], 2, s[50:51]
	v_cmp_gt_i32_e32 vcc, s84, v176
	v_lshl_add_u64 v[4:5], v[4:5], 0, s[2:3]
	s_nop 1
	v_cndmask_b32_e32 v5, v5, v1, vcc
	v_cndmask_b32_e32 v4, v4, v0, vcc
	global_load_dword v62, v[4:5], off
	v_add_u32_e32 v176, 0x200, v176
	v_lshl_add_u64 v[0:1], v[0:1], 0, s[72:73]
	v_lshl_add_u64 v[4:5], v[176:177], 2, s[50:51]
	v_cmp_gt_i32_e32 vcc, s84, v176
	v_lshl_add_u64 v[4:5], v[4:5], 0, s[2:3]
	s_nop 1
	v_cndmask_b32_e32 v5, v5, v1, vcc
	v_cndmask_b32_e32 v4, v4, v0, vcc
	global_load_dword v64, v[4:5], off
	v_add_u32_e32 v176, 0x200, v176
	v_lshl_add_u64 v[0:1], v[0:1], 0, s[72:73]
	v_lshl_add_u64 v[4:5], v[176:177], 2, s[50:51]
	v_cmp_gt_i32_e32 vcc, s84, v176
	v_lshl_add_u64 v[4:5], v[4:5], 0, s[2:3]
	s_nop 1
	v_cndmask_b32_e32 v5, v5, v1, vcc
	v_cndmask_b32_e32 v4, v4, v0, vcc
	global_load_dword v66, v[4:5], off
	v_add_u32_e32 v176, 0x200, v176
	v_lshl_add_u64 v[0:1], v[0:1], 0, s[72:73]
	v_lshl_add_u64 v[4:5], v[176:177], 2, s[50:51]
	v_cmp_gt_i32_e32 vcc, s84, v176
	v_lshl_add_u64 v[4:5], v[4:5], 0, s[2:3]
	s_nop 1
	v_cndmask_b32_e32 v5, v5, v1, vcc
	v_cndmask_b32_e32 v4, v4, v0, vcc
	global_load_dword v112, v[4:5], off
	v_add_u32_e32 v176, 0x200, v176
	v_lshl_add_u64 v[0:1], v[0:1], 0, s[72:73]
	v_lshl_add_u64 v[4:5], v[176:177], 2, s[50:51]
	v_cmp_gt_i32_e32 vcc, s84, v176
	v_lshl_add_u64 v[4:5], v[4:5], 0, s[2:3]
	s_nop 1
	v_cndmask_b32_e32 v5, v5, v1, vcc
	v_cndmask_b32_e32 v4, v4, v0, vcc
	global_load_dword v114, v[4:5], off
	v_add_u32_e32 v176, 0x200, v176
	v_lshl_add_u64 v[0:1], v[0:1], 0, s[72:73]
	s_waitcnt vmcnt(0)
	v_mul_f32_e32 v5, 0xbfb8aa3b, v52
	v_exp_f32_e32 v5, v5
	s_nop 0
	v_add_f32_e32 v5, 1.0, v5
	v_rcp_f32_e32 v5, v5
	s_nop 0
	v_mul_f32_e32 v3, v52, v5
	ds_write_b32 v2, v3
	v_add_u32_e32 v2, 0x800, v2
	v_mul_f32_e32 v5, 0xbfb8aa3b, v54
	v_exp_f32_e32 v5, v5
	s_nop 0
	v_add_f32_e32 v5, 1.0, v5
	v_rcp_f32_e32 v5, v5
	s_nop 0
	v_mul_f32_e32 v3, v54, v5
	ds_write_b32 v2, v3
	v_add_u32_e32 v2, 0x800, v2
	v_mul_f32_e32 v5, 0xbfb8aa3b, v56
	v_exp_f32_e32 v5, v5
	s_nop 0
	v_add_f32_e32 v5, 1.0, v5
	v_rcp_f32_e32 v5, v5
	s_nop 0
	v_mul_f32_e32 v3, v56, v5
	ds_write_b32 v2, v3
	v_add_u32_e32 v2, 0x800, v2
	v_mul_f32_e32 v5, 0xbfb8aa3b, v58
	v_exp_f32_e32 v5, v5
	s_nop 0
	v_add_f32_e32 v5, 1.0, v5
	v_rcp_f32_e32 v5, v5
	s_nop 0
	v_mul_f32_e32 v3, v58, v5
	ds_write_b32 v2, v3
	v_add_u32_e32 v2, 0x800, v2
	v_mul_f32_e32 v5, 0xbfb8aa3b, v60
	v_exp_f32_e32 v5, v5
	s_nop 0
	v_add_f32_e32 v5, 1.0, v5
	v_rcp_f32_e32 v5, v5
	s_nop 0
	v_mul_f32_e32 v3, v60, v5
	ds_write_b32 v2, v3
	v_add_u32_e32 v2, 0x800, v2
	v_mul_f32_e32 v5, 0xbfb8aa3b, v62
	v_exp_f32_e32 v5, v5
	s_nop 0
	v_add_f32_e32 v5, 1.0, v5
	v_rcp_f32_e32 v5, v5
	s_nop 0
	v_mul_f32_e32 v3, v62, v5
	ds_write_b32 v2, v3
	v_add_u32_e32 v2, 0x800, v2
	v_mul_f32_e32 v5, 0xbfb8aa3b, v64
	v_exp_f32_e32 v5, v5
	s_nop 0
	v_add_f32_e32 v5, 1.0, v5
	v_rcp_f32_e32 v5, v5
	s_nop 0
	v_mul_f32_e32 v3, v64, v5
	ds_write_b32 v2, v3
	v_add_u32_e32 v2, 0x800, v2
	v_mul_f32_e32 v5, 0xbfb8aa3b, v66
	v_exp_f32_e32 v5, v5
	s_nop 0
	v_add_f32_e32 v5, 1.0, v5
	v_rcp_f32_e32 v5, v5
	s_nop 0
	v_mul_f32_e32 v3, v66, v5
	ds_write_b32 v2, v3
	v_add_u32_e32 v2, 0x800, v2
; __device__ __forceinline__ float silu_f(float x) { return x * sigm_f(x); }
; __global__ void __launch_bounds__(512, 2) mega_fwd(Args args) {
;     ...
;                 for (int i = tid; i < 5 * DM; i += 512) { const float v = i < 4 * DM ? args.in[1][i] : args.in[3][i - 4 * DM]; sc[i] = silu_f(v); }
	v_mul_f32_e32 v5, 0xbfb8aa3b, v112
	v_exp_f32_e32 v5, v5
	s_nop 0
	v_add_f32_e32 v5, 1.0, v5
	v_rcp_f32_e32 v5, v5
	s_nop 0
	v_mul_f32_e32 v3, v112, v5
	ds_write_b32 v2, v3
	v_add_u32_e32 v2, 0x800, v2
	v_mul_f32_e32 v5, 0xbfb8aa3b, v114
	v_exp_f32_e32 v5, v5
	s_nop 0
	v_add_f32_e32 v5, 1.0, v5
	v_rcp_f32_e32 v5, v5
	s_nop 0
	v_mul_f32_e32 v3, v114, v5
	ds_write_b32 v2, v3
	v_add_u32_e32 v2, 0x800, v2
	v_lshl_add_u64 v[4:5], v[176:177], 2, s[50:51]
	v_cmp_gt_i32_e32 vcc, s84, v176
	v_lshl_add_u64 v[4:5], v[4:5], 0, s[2:3]
	s_nop 1
	v_cndmask_b32_e32 v5, v5, v1, vcc
	v_cndmask_b32_e32 v4, v4, v0, vcc
	global_load_dword v52, v[4:5], off
	v_add_u32_e32 v176, 0x200, v176
	v_lshl_add_u64 v[0:1], v[0:1], 0, s[72:73]
	v_lshl_add_u64 v[4:5], v[176:177], 2, s[50:51]
	v_cmp_gt_i32_e32 vcc, s84, v176
	v_lshl_add_u64 v[4:5], v[4:5], 0, s[2:3]
	s_nop 1
	v_cndmask_b32_e32 v5, v5, v1, vcc
	v_cndmask_b32_e32 v4, v4, v0, vcc
	global_load_dword v54, v[4:5], off
	v_add_u32_e32 v176, 0x200, v176
	v_lshl_add_u64 v[0:1], v[0:1], 0, s[72:73]
	v_lshl_add_u64 v[4:5], v[176:177], 2, s[50:51]
	v_cmp_gt_i32_e32 vcc, s84, v176
	v_lshl_add_u64 v[4:5], v[4:5], 0, s[2:3]
	s_nop 1
	v_cndmask_b32_e32 v5, v5, v1, vcc
	v_cndmask_b32_e32 v4, v4, v0, vcc
	global_load_dword v56, v[4:5], off
	v_add_u32_e32 v176, 0x200, v176
	v_lshl_add_u64 v[0:1], v[0:1], 0, s[72:73]
	v_lshl_add_u64 v[4:5], v[176:177], 2, s[50:51]
	v_cmp_gt_i32_e32 vcc, s84, v176
	v_lshl_add_u64 v[4:5], v[4:5], 0, s[2:3]
	s_nop 1
	v_cndmask_b32_e32 v5, v5, v1, vcc
	v_cndmask_b32_e32 v4, v4, v0, vcc
	global_load_dword v58, v[4:5], off
	v_add_u32_e32 v176, 0x200, v176
	v_lshl_add_u64 v[0:1], v[0:1], 0, s[72:73]
	v_lshl_add_u64 v[4:5], v[176:177], 2, s[50:51]
	v_cmp_gt_i32_e32 vcc, s84, v176
	v_lshl_add_u64 v[4:5], v[4:5], 0, s[2:3]
	s_nop 1
	v_cndmask_b32_e32 v5, v5, v1, vcc
	v_cndmask_b32_e32 v4, v4, v0, vcc
	global_load_dword v60, v[4:5], off
	v_add_u32_e32 v176, 0x200, v176
	v_lshl_add_u64 v[0:1], v[0:1], 0, s[72:73]
	v_lshl_add_u64 v[4:5], v[176:177], 2, s[50:51]
	v_cmp_gt_i32_e32 vcc, s84, v176
	v_lshl_add_u64 v[4:5], v[4:5], 0, s[2:3]
	s_nop 1
	v_cndmask_b32_e32 v5, v5, v1, vcc
	v_cndmask_b32_e32 v4, v4, v0, vcc
	global_load_dword v62, v[4:5], off
	v_add_u32_e32 v176, 0x200, v176
	v_lshl_add_u64 v[0:1], v[0:1], 0, s[72:73]
	v_lshl_add_u64 v[4:5], v[176:177], 2, s[50:51]
	v_cmp_gt_i32_e32 vcc, s84, v176
	v_lshl_add_u64 v[4:5], v[4:5], 0, s[2:3]
	s_nop 1
	v_cndmask_b32_e32 v5, v5, v1, vcc
	v_cndmask_b32_e32 v4, v4, v0, vcc
	global_load_dword v64, v[4:5], off
	v_add_u32_e32 v176, 0x200, v176
	v_lshl_add_u64 v[0:1], v[0:1], 0, s[72:73]
	v_lshl_add_u64 v[4:5], v[176:177], 2, s[50:51]
	v_cmp_gt_i32_e32 vcc, s84, v176
	v_lshl_add_u64 v[4:5], v[4:5], 0, s[2:3]
	s_nop 1
	v_cndmask_b32_e32 v5, v5, v1, vcc
	v_cndmask_b32_e32 v4, v4, v0, vcc
	global_load_dword v66, v[4:5], off
	v_add_u32_e32 v176, 0x200, v176
	v_lshl_add_u64 v[0:1], v[0:1], 0, s[72:73]
	v_lshl_add_u64 v[4:5], v[176:177], 2, s[50:51]
	v_cmp_gt_i32_e32 vcc, s84, v176
	v_lshl_add_u64 v[4:5], v[4:5], 0, s[2:3]
	s_nop 1
	v_cndmask_b32_e32 v5, v5, v1, vcc
	v_cndmask_b32_e32 v4, v4, v0, vcc
	global_load_dword v112, v[4:5], off
	v_add_u32_e32 v176, 0x200, v176
	v_lshl_add_u64 v[0:1], v[0:1], 0, s[72:73]
	v_lshl_add_u64 v[4:5], v[176:177], 2, s[50:51]
	v_cmp_gt_i32_e32 vcc, s84, v176
	v_lshl_add_u64 v[4:5], v[4:5], 0, s[2:3]
	s_nop 1
	v_cndmask_b32_e32 v5, v5, v1, vcc
	v_cndmask_b32_e32 v4, v4, v0, vcc
	global_load_dword v114, v[4:5], off
	v_add_u32_e32 v176, 0x200, v176
	v_lshl_add_u64 v[0:1], v[0:1], 0, s[72:73]
	s_waitcnt vmcnt(0)
	v_mul_f32_e32 v5, 0xbfb8aa3b, v52
	v_exp_f32_e32 v5, v5
	s_nop 0
	v_add_f32_e32 v5, 1.0, v5
	v_rcp_f32_e32 v5, v5
	s_nop 0
	v_mul_f32_e32 v3, v52, v5
	ds_write_b32 v2, v3
	v_add_u32_e32 v2, 0x800, v2
	v_mul_f32_e32 v5, 0xbfb8aa3b, v54
	v_exp_f32_e32 v5, v5
	s_nop 0
	v_add_f32_e32 v5, 1.0, v5
	v_rcp_f32_e32 v5, v5
	s_nop 0
	v_mul_f32_e32 v3, v54, v5
	ds_write_b32 v2, v3
	v_add_u32_e32 v2, 0x800, v2
	v_mul_f32_e32 v5, 0xbfb8aa3b, v56
	v_exp_f32_e32 v5, v5
	s_nop 0
	v_add_f32_e32 v5, 1.0, v5
	v_rcp_f32_e32 v5, v5
	s_nop 0
	v_mul_f32_e32 v3, v56, v5
	ds_write_b32 v2, v3
	v_add_u32_e32 v2, 0x800, v2
	v_mul_f32_e32 v5, 0xbfb8aa3b, v58
	v_exp_f32_e32 v5, v5
	s_nop 0
	v_add_f32_e32 v5, 1.0, v5
	v_rcp_f32_e32 v5, v5
	s_nop 0
	v_mul_f32_e32 v3, v58, v5
	ds_write_b32 v2, v3
	v_add_u32_e32 v2, 0x800, v2
	v_mul_f32_e32 v5, 0xbfb8aa3b, v60
	v_exp_f32_e32 v5, v5
	s_nop 0
	v_add_f32_e32 v5, 1.0, v5
	v_rcp_f32_e32 v5, v5
	s_nop 0
	v_mul_f32_e32 v3, v60, v5
	ds_write_b32 v2, v3
	v_add_u32_e32 v2, 0x800, v2
	v_mul_f32_e32 v5, 0xbfb8aa3b, v62
	v_exp_f32_e32 v5, v5
	s_nop 0
	v_add_f32_e32 v5, 1.0, v5
	v_rcp_f32_e32 v5, v5
	s_nop 0
	v_mul_f32_e32 v3, v62, v5
	ds_write_b32 v2, v3
	v_add_u32_e32 v2, 0x800, v2
	v_mul_f32_e32 v5, 0xbfb8aa3b, v64
	v_exp_f32_e32 v5, v5
	s_nop 0
	v_add_f32_e32 v5, 1.0, v5
	v_rcp_f32_e32 v5, v5
	s_nop 0
	v_mul_f32_e32 v3, v64, v5
	ds_write_b32 v2, v3
	v_add_u32_e32 v2, 0x800, v2
	v_mul_f32_e32 v5, 0xbfb8aa3b, v66
	v_exp_f32_e32 v5, v5
	s_nop 0
	v_add_f32_e32 v5, 1.0, v5
	v_rcp_f32_e32 v5, v5
	s_nop 0
	v_mul_f32_e32 v3, v66, v5
	ds_write_b32 v2, v3
	v_add_u32_e32 v2, 0x800, v2
	v_mul_f32_e32 v5, 0xbfb8aa3b, v112
	v_exp_f32_e32 v5, v5
	s_nop 0
	v_add_f32_e32 v5, 1.0, v5
	v_rcp_f32_e32 v5, v5
	s_nop 0
	v_mul_f32_e32 v3, v112, v5
	ds_write_b32 v2, v3
	v_add_u32_e32 v2, 0x800, v2
	v_mul_f32_e32 v5, 0xbfb8aa3b, v114
	v_exp_f32_e32 v5, v5
	s_nop 0
	v_add_f32_e32 v5, 1.0, v5
	v_rcp_f32_e32 v5, v5
	s_nop 0
	v_mul_f32_e32 v3, v114, v5
	ds_write_b32 v2, v3
	v_add_u32_e32 v2, 0x800, v2
